# v66 + epilogue-entry waits of in-proj and up GEMMs lowered from vmcnt(0) to vmcnt(8): only the unit's prefetched constants are needed, not the next unit's DMAs
# speedup vs baseline: 1.0081x; 1.0081x over previous
; #define PG8_LAS __attribute__((address_space(3)))
; __device__ __forceinline__ float rstd_ss(float ss) { return __builtin_amdgcn_rsqf(ss * (1.0f / 2048.0f) + 1e-6f); }
; __device__ __forceinline__ f32x4 pre_row_read(const PG8_LAS float* L, int ai, int wr, int fr) {
;     const f32x4 s0 = *(const PG8_LAS f32x4*)(L + (ai * 2 + wr) * 64 + 4 * fr), s1 = *(const PG8_LAS f32x4*)(L + 256 + (ai * 2 + wr) * 64 + 4 * fr);
;     return (f32x4){rstd_ss(s0[0] + s1[0]), rstd_ss(s0[1] + s1[1]), rstd_ss(s0[2] + s1[2]), rstd_ss(s0[3] + s1[3])}; }
;     __device__ __forceinline__ void operator()(const f32x4 (&acc)[2][2][4][2], const Unit& u, int wr, int wc, int fr, int fq, const Pre& pre, PG8_LAS unsigned char* lds, int tid) const {
;         const int row0 = u.pm * BM + wr * 64 + fr; int colt = u.pn * BM; bf16_t* base = O; bool act = false;
;         if (MODE == 1) { if (u.pn >= 8) { base = O2; colt -= 2048; } else act = true; }
;         const int col0 = colt + wc * 32 + 8 * fq;
;         PG8_LAS float* L = (PG8_LAS float*)(lds + 131072);
;         pre_row_publish(L, pre.r, tid);
;         if (MODE == 1 && tid < 256) L[512 + tid] = pre.c;
;         asm volatile("s_waitcnt lgkmcnt(0)" ::: "memory"); __builtin_amdgcn_s_barrier(); asm volatile("" ::: "memory");
;         f32x4 bv[2][2]; f32x4 rsv[2];
; #pragma unroll
;         for (int bj = 0; bj < 2; ++bj)
; #pragma unroll
;             for (int n = 0; n < 2; ++n) bv[bj][n] = (MODE == 1) ? *(const PG8_LAS f32x4*)(L + 512 + bj * HALF + wc * 32 + 8 * fq + 4 * n) : (f32x4){0.f, 0.f, 0.f, 0.f};
; #pragma unroll
;         for (int ai = 0; ai < 2; ++ai) rsv[ai] = pre_row_read(L, ai, wr, fr);
; #pragma unroll
;         for (int ai = 0; ai < 2; ++ai)
; #pragma unroll
;             for (int m = 0; m < 4; ++m) { bf16_t* rowp = base + (size_t)(row0 + ai * HALF + m * 16) * ldc + col0; const float rs = rsv[ai][m];
; #pragma unroll
;                 for (int bj = 0; bj < 2; ++bj) { f32x4 v0 = acc[ai][bj][m][0] * rs + bv[bj][0], v1 = acc[ai][bj][m][1] * rs + bv[bj][1];
;                     if (MODE == 1) { if (act) {
; #pragma unroll
;                         for (int e = 0; e < 1; ++e) { v0 = gelu_tanh4(v0); v1 = gelu_tanh4(v1); } } }
.LBB0_180:
	s_waitcnt vmcnt(8)
	v_mov_b32_e32 v60, v51
	v_mov_b32_e32 v61, v52
	v_mov_b32_e32 v51, v53
	v_pk_add_f32 v[50:51], v[60:61], v[50:51]
	s_nop 0
	v_add_f32_e32 v50, v50, v51
	ds_write_b32 v195, v50
	s_and_saveexec_b64 s[12:13], s[38:39]
	ds_write_b32 v196, v58 offset:2048
	s_or_b64 exec, exec, s[12:13]
	s_waitcnt lgkmcnt(0)
	s_barrier
	ds_read_b128 v[154:157], v198
	ds_read_b128 v[158:161], v199
	ds_read_b128 v[74:77], v197
	ds_read_b128 v[82:85], v198 offset:512
	ds_read_b128 v[86:89], v199 offset:512
	s_cmp_lt_i32 s66, 8
	s_cselect_b64 s[12:13], -1, 0
	s_cmp_gt_i32 s66, 7
	s_waitcnt lgkmcnt(0)
	v_add_f32_e32 v50, v154, v158
	v_fmamk_f32 v50, v50, 0x3a000000, v220
	v_rsq_f32_e32 v174, v50
	ds_read_b128 v[66:69], v197 offset:16
	ds_read_b128 v[58:61], v197 offset:512
	ds_read_b128 v[50:53], v197 offset:528
	v_pk_fma_f32 v[152:153], v[152:153], v[174:175], v[76:77] op_sel_hi:[1,0,1]
	v_pk_fma_f32 v[178:179], v[150:151], v[174:175], v[74:75] op_sel_hi:[1,0,1]
	s_waitcnt lgkmcnt(2)
	v_pk_fma_f32 v[176:177], v[148:149], v[174:175], v[68:69] op_sel_hi:[1,0,1]
	v_pk_fma_f32 v[180:181], v[146:147], v[174:175], v[66:67] op_sel_hi:[1,0,1]
	s_cbranch_scc1 .LBB0_184
	s_mov_b32 s14, 0xc0135761
	v_pk_mul_f32 v[146:147], v[152:153], v[152:153]
	v_pk_mul_f32 v[148:149], v[178:179], v[178:179]
	v_mov_b64_e32 v[150:151], s[14:15]
	v_pk_fma_f32 v[146:147], v[146:147], s[8:9], v[150:151] op_sel_hi:[1,0,0] neg_lo:[1,0,0] neg_hi:[1,0,0]
	v_pk_fma_f32 v[148:149], v[148:149], s[8:9], v[150:151] op_sel_hi:[1,0,0] neg_lo:[1,0,0] neg_hi:[1,0,0]
	v_pk_mul_f32 v[146:147], v[152:153], v[146:147]
	v_pk_mul_f32 v[148:149], v[178:179], v[148:149]
	v_exp_f32_e32 v146, v146
	v_exp_f32_e32 v148, v148
	v_exp_f32_e32 v149, v149
	v_exp_f32_e32 v147, v147
	v_pk_add_f32 v[148:149], v[148:149], 1.0 op_sel_hi:[1,0]
	v_pk_add_f32 v[146:147], v[146:147], 1.0 op_sel_hi:[1,0]
	v_rcp_f32_e32 v148, v148
	v_rcp_f32_e32 v149, v149
	v_rcp_f32_e32 v146, v146
	v_rcp_f32_e32 v147, v147
	v_pk_mul_f32 v[178:179], v[178:179], v[148:149]
	v_pk_mul_f32 v[148:149], v[180:181], v[180:181]
	v_pk_mul_f32 v[152:153], v[152:153], v[146:147]
	v_pk_mul_f32 v[146:147], v[176:177], v[176:177]
	v_pk_fma_f32 v[148:149], v[148:149], s[8:9], v[150:151] op_sel_hi:[1,0,0] neg_lo:[1,0,0] neg_hi:[1,0,0]
	v_pk_fma_f32 v[146:147], v[146:147], s[8:9], v[150:151] op_sel_hi:[1,0,0] neg_lo:[1,0,0] neg_hi:[1,0,0]
	v_pk_mul_f32 v[148:149], v[180:181], v[148:149]
	v_pk_mul_f32 v[146:147], v[176:177], v[146:147]
	v_exp_f32_e32 v148, v148
	v_exp_f32_e32 v149, v149
	v_exp_f32_e32 v146, v146
	v_exp_f32_e32 v147, v147
	v_pk_add_f32 v[148:149], v[148:149], 1.0 op_sel_hi:[1,0]
	s_nop 0
	v_rcp_f32_e32 v148, v148
	v_pk_add_f32 v[146:147], v[146:147], 1.0 op_sel_hi:[1,0]
	v_rcp_f32_e32 v149, v149
	v_rcp_f32_e32 v146, v146
	v_rcp_f32_e32 v147, v147
	v_pk_mul_f32 v[180:181], v[180:181], v[148:149]
	v_pk_mul_f32 v[176:177], v[176:177], v[146:147]

; #define PG8_LAS __attribute__((address_space(3)))
; __device__ __forceinline__ float rstd_ss(float ss) { return __builtin_amdgcn_rsqf(ss * (1.0f / 2048.0f) + 1e-6f); }
;     __device__ __forceinline__ void operator()(const f32x4 (&acc)[2][2][4][2], const Unit& u, int wr, int wc, int fr, int fq, const Pre& pre, PG8_LAS unsigned char* lds, int tid) const {
;         const int gcol = u.pn * 128 + wc * 32 + 8 * fq;
;         PG8_LAS float* L = (PG8_LAS float*)(lds + 131072);
;         if (tid < 256) L[tid] = rstd_ss(((pre.a[0] + pre.a[1]) + (pre.a[2] + pre.a[3])) + ((pre.b[0] + pre.b[1]) + (pre.b[2] + pre.b[3])));
;         else *(PG8_LAS f32x4*)(L + 256 + (tid - 256) * 4) = pre.a;
;         asm volatile("s_waitcnt lgkmcnt(0)" ::: "memory"); __builtin_amdgcn_s_barrier(); asm volatile("" ::: "memory");
;         float rs[2][4];
; #pragma unroll
;         for (int ai = 0; ai < 2; ++ai) { const f32x4 r = *(const PG8_LAS f32x4*)(L + (ai * 2 + wr) * 64 + 4 * fr);
; #pragma unroll
;             for (int m = 0; m < 4; ++m) rs[ai][m] = r[m]; }
;         const PG8_LAS float* LW = L + 256 + wc * 32 + 8 * fq;
;         if (fr == 0 || fr == 15) { const bool hi = fr == 15;
.LBB0_786:
	s_waitcnt vmcnt(8)
	v_mov_b32_e32 v138, v78
	v_mov_b32_e32 v139, v74
	v_mov_b32_e32 v74, v79
	v_mov_b32_e32 v78, v80
	v_mov_b32_e32 v79, v76
	v_mov_b32_e32 v76, v81
	v_pk_add_f32 v[74:75], v[138:139], v[74:75]
	v_pk_add_f32 v[76:77], v[78:79], v[76:77]
	v_readlane_b32 s11, v255, 0
	v_pk_add_f32 v[74:75], v[74:75], v[76:77]
	s_nop 0
	v_add_f32_e32 v74, v74, v75
	v_fmamk_f32 v74, v74, 0x3a000000, v220
	v_rsq_f32_e32 v74, v74
	v_lshl_add_u32 v75, v177, 2, s11
	ds_write_b32 v75, v74
.LBB0_787:
	s_or_b64 exec, exec, s[14:15]
	s_waitcnt lgkmcnt(0)
	s_barrier
	s_waitcnt vmcnt(8)
	ds_read_b128 v[78:81], v212
	ds_read_b128 v[74:77], v212 offset:512
	v_lshl_add_u32 v194, s12, 7, v209
	v_cmp_gt_i32_e32 vcc, 15, v206
	s_mov_b64 s[14:15], -1
	s_and_saveexec_b64 s[12:13], vcc
	s_cbranch_execz .LBB0_791
	v_cmp_eq_u32_e32 vcc, 0, v206
	v_cmp_ne_u32_e64 s[46:47], 0, v206
	s_and_saveexec_b64 s[14:15], s[46:47]
	v_ashrrev_i32_e32 v195, 31, v194
	s_or_b64 exec, exec, s[14:15]
	s_orn2_b64 s[14:15], vcc, exec

; #define PG8_LAS __attribute__((address_space(3)))
; __device__ __forceinline__ float rstd_ss(float ss) { return __builtin_amdgcn_rsqf(ss * (1.0f / 2048.0f) + 1e-6f); }
;     __device__ __forceinline__ void operator()(const f32x4 (&acc)[2][2][4][2], const Unit& u, int wr, int wc, int fr, int fq, const Pre& pre, PG8_LAS unsigned char* lds, int tid) const {
;     ...
;         if (tid < 256) L[tid] = rstd_ss(((pre.a[0] + pre.a[1]) + (pre.a[2] + pre.a[3])) + ((pre.b[0] + pre.b[1]) + (pre.b[2] + pre.b[3])));
;         else *(PG8_LAS f32x4*)(L + 256 + (tid - 256) * 4) = pre.a;
;         asm volatile("s_waitcnt lgkmcnt(0)" ::: "memory"); __builtin_amdgcn_s_barrier(); asm volatile("" ::: "memory");
.LBB0_812:
	s_waitcnt vmcnt(8)
	v_add_u32_e32 v78, 0, v179
	v_add_u32_e32 v78, 0x1f400, v78
	ds_write_b128 v78, v[74:77]
	s_andn2_saveexec_b64 s[14:15], s[14:15]
	s_cbranch_execnz .LBB0_786
	s_branch .LBB0_787
